# P8 epilogue: tap pre-scaling moved ahead of the halo barrier (no vector ALU work at the head of the segment behind it)
# speedup vs baseline: 1.0016x; 1.0016x over previous
; #define PG8_LAS __attribute__((address_space(3)))
;     __device__ __forceinline__ void operator()(const f32x4 (&acc)[2][2][4][2], const Unit& u, int wr, int wc, int fr, int fq) const {
;         const int lane = threadIdx.x & 63;
;         const int j0 = 128 * u.pn + 32 * wc + 2 * fr;
;         float wa[2][3], wb[2][3], ba[2], bb[2];
;         {
;             f32x2_t ta[3], tb[3];
; #pragma unroll
;             for (int k = 0; k < 3; ++k) { ta[k] = *(const f32x2_t*)(cw + k * NUP + j0); tb[k] = *(const f32x2_t*)(cw + k * NUP + DFF + j0); }
;             const f32x2_t tba = *(const f32x2_t*)(cb + j0), tbb = *(const f32x2_t*)(cb + DFF + j0);
; #pragma unroll
;             for (int n = 0; n < 2; ++n) {
; #pragma unroll
;                 for (int k = 0; k < 3; ++k) { wa[n][k] = ta[k][n]; wb[n][k] = tb[k][n]; }
;                 ba[n] = tba[n]; bb[n] = tbb[n]; }
;         }
;         if (fq == 3) {
; #pragma unroll
;             for (int ai = 0; ai < 2; ++ai)
; #pragma unroll
;                 for (int bj = 0; bj < 2; ++bj)
; #pragma unroll
;                     for (int n = 0; n < 2; ++n) { PG8_LAS float* hp = halo + (((((ai * 2 + wr) * 4 + wc) * 2 + bj) * 2 + n) * 32) + fr; hp[0] = acc[ai][bj][3][n][2]; hp[16] = acc[ai][bj][3][n][3]; }
;         }
;         asm volatile("s_waitcnt lgkmcnt(0)" ::: "memory"); __builtin_amdgcn_s_barrier(); asm volatile("" ::: "memory");
.LBB0_889:
	v_readfirstlane_b32 s19, v195
	v_and_b32_e32 v190, 15, v195
	v_bfe_u32 v191, v195, 4, 2
	s_lshr_b32 s19, s19, 6
	s_and_b32 s24, s19, 3
	s_lshr_b32 s25, s19, 2
	v_lshrrev_b32_e32 v192, 2, v237
	s_lshl_b32 s27, s25, 6
	v_lshl_add_u32 v193, v191, 2, s27
	v_mul_u32_u24_e32 v193, 0x1600, v193
	v_lshl_add_u32 v157, v192, 1, v193
	v_add_u32_e32 v158, 48, v195
	v_and_b32_e32 v158, 63, v158
	v_lshlrev_b32_e32 v158, 2, v158
	s_lshl_b32 s27, s25, 11
	s_lshl_b32 s17, s24, 9
	s_add_i32 s27, s27, s17
	s_add_i32 s27, s27, 0x20400
	v_lshl_add_u32 v159, v190, 2, s27
	v_add_u32_e32 v160, 0xfffff800, v159
	v_mov_b32_e32 v162, 1.0
	v_mov_b32_e32 v163, 1.0
	v_mul_f32_e32 v238, 0xbfb8aa3b, v238
	v_mul_f32_e32 v239, 0xbfb8aa3b, v239
	v_mul_f32_e32 v244, 0xbf317218, v244
	v_mul_f32_e32 v245, 0xbf317218, v245
	v_mul_f32_e32 v240, 0xbfb8aa3b, v240
	v_mul_f32_e32 v241, 0xbfb8aa3b, v241
	v_mul_f32_e32 v246, 0xbf317218, v246
	v_mul_f32_e32 v247, 0xbf317218, v247
	v_mul_f32_e32 v242, 0xbfb8aa3b, v242
	v_mul_f32_e32 v243, 0xbfb8aa3b, v243
	v_mul_f32_e32 v248, 0xbf317218, v248
	v_mul_f32_e32 v249, 0xbf317218, v249
	v_mul_f32_e32 v250, 0xbfb8aa3b, v250
	v_mul_f32_e32 v251, 0xbfb8aa3b, v251
	v_mul_f32_e32 v252, 0xbf317218, v252
	v_mul_f32_e32 v253, 0xbf317218, v253
	s_and_saveexec_b64 s[16:17], s[6:7]
	ds_write_b32 v159, v70
	ds_write_b32 v159, v71 offset:64
	ds_write_b32 v159, v78 offset:128
	ds_write_b32 v159, v79 offset:192
	ds_write_b32 v159, v66 offset:256
	ds_write_b32 v159, v67 offset:320
	ds_write_b32 v159, v74 offset:384
	ds_write_b32 v159, v75 offset:448
	ds_write_b32 v159, v2 offset:4096
	ds_write_b32 v159, v3 offset:4160
	ds_write_b32 v159, v14 offset:4224
	ds_write_b32 v159, v15 offset:4288
	ds_write_b32 v159, v6 offset:4352
	ds_write_b32 v159, v7 offset:4416
	s_waitcnt lgkmcnt(13)
	ds_write_b32 v159, v10 offset:4480
	s_waitcnt lgkmcnt(13)
	ds_write_b32 v159, v11 offset:4544
	s_or_b64 exec, exec, s[16:17]
	s_waitcnt lgkmcnt(0)
	s_barrier
	s_cmp_eq_u32 s25, 0
	s_cbranch_scc1 .Lp8_nohalo
	ds_read_b32 v228, v160
	ds_read_b32 v229, v160 offset:64
	ds_read_b32 v230, v160 offset:256
	ds_read_b32 v231, v160 offset:320
	ds_read_b32 v232, v160 offset:128
	ds_read_b32 v233, v160 offset:192
	ds_read_b32 v234, v160 offset:384
	ds_read_b32 v235, v160 offset:448
	s_branch .Lp8_halo_done

; __device__ __forceinline__ float silu_f(float x) { return x * __builtin_amdgcn_rcpf(1.0f + __builtin_amdgcn_exp2f(-1.4426950408889634f * x)); }
; #define PG8_LAS __attribute__((address_space(3)))
;     __device__ __forceinline__ void operator()(const f32x4 (&acc)[2][2][4][2], const Unit& u, int wr, int wc, int fr, int fq) const {
;     ...
;                     float Ha2 = __builtin_bit_cast(float, __builtin_amdgcn_ds_bpermute(src, __builtin_bit_cast(int, da2)));
;                     float Ha3 = __builtin_bit_cast(float, __builtin_amdgcn_ds_bpermute(src, __builtin_bit_cast(int, da3)));
;                     float Hb2 = __builtin_bit_cast(float, __builtin_amdgcn_ds_bpermute(src, __builtin_bit_cast(int, db2)));
;                     float Hb3 = __builtin_bit_cast(float, __builtin_amdgcn_ds_bpermute(src, __builtin_bit_cast(int, db3)));
;                     if (m == 0) {
;                         float h2a = 0.f, h3a = 0.f, h2b = 0.f, h3b = 0.f;
;                         if (blk > 0) { const PG8_LAS float* hp = halo + ((((blk - 1) * 4 + wc) * 2 + 0) * 2 + n) * 32 + fr; h2a = hp[0]; h3a = hp[16]; h2b = hp[64]; h3b = hp[80]; }
;                         if (fq == 0) { Ha2 = h2a; Ha3 = h3a; Hb2 = h2b; Hb3 = h3b; }
;                     }
;                     const f32x2_t W0 = {wa[n][0], wb[n][0]}, W1 = {wa[n][1], wb[n][1]}, W2 = {wa[n][2], wb[n][2]}, B2 = {ba[n], bb[n]};
;                     const f32x2_t H2 = {Ha2, Hb2}, H3 = {Ha3, Hb3}, X0 = {Xa[0], Xb[0]}, X1 = {Xa[1], Xb[1]}, X2 = {Xa[2], Xb[2]}, X3 = {Xa[3], Xb[3]};
;                     const f32x2_t y0 = B2 + W0 * H2 + W1 * H3 + W2 * X0, y1 = B2 + W0 * H3 + W1 * X0 + W2 * X1, y2 = B2 + W0 * X0 + W1 * X1 + W2 * X2, y3 = B2 + W0 * X1 + W1 * X2 + W2 * X3;
;                     const float ya0 = y0[0], yb0 = y0[1], ya1 = y1[0], yb1 = y1[1], ya2 = y2[0], yb2 = y2[1], ya3 = y3[0], yb3 = y3[1];
;                     o[n][0] = silu_f(ya0) * yb0; o[n][1] = silu_f(ya1) * yb1; o[n][2] = silu_f(ya2) * yb2; o[n][3] = silu_f(ya3) * yb3;
;                     if (blk == 0 && m == 0 && fq == 0) { float* sp = SIDE + ((size_t)(u.pm * 4 + 0) * 2) * DFF + j0 + n; sp[0] = Xa[0]; sp[DFF] = Xb[0]; sp[2 * DFF] = Xa[1]; sp[3 * DFF] = Xb[1]; }
.Lp8_halo_done:
	ds_bpermute_b32 v196, v158, v126
	ds_bpermute_b32 v197, v158, v127
	ds_bpermute_b32 v198, v158, v122
	ds_bpermute_b32 v199, v158, v123
	ds_bpermute_b32 v200, v158, v118
	ds_bpermute_b32 v201, v158, v119
	s_waitcnt lgkmcnt(13)
	ds_bpermute_b32 v202, v158, v114
	s_waitcnt lgkmcnt(13)
	ds_bpermute_b32 v203, v158, v115
	s_mul_i32 s26, s74, 0x16000
	s_add_u32 s26, s87, s26
	s_addc_u32 s27, s88, 0
	s_cmp_eq_u32 s25, 0
	s_cbranch_scc0 .Lp8_side_hi
	s_and_saveexec_b64 s[16:17], s[8:9]
	global_store_dword v237, v124, s[26:27]
	global_store_dword v237, v116, s[26:27] offset:4
	s_add_u32 s26, s26, 0x2c00
	s_addc_u32 s27, s27, 0
	global_store_dword v237, v120, s[26:27]
	global_store_dword v237, v112, s[26:27] offset:4
	s_add_u32 s26, s26, 0x2c00
	s_addc_u32 s27, s27, 0
	global_store_dword v237, v125, s[26:27]
	global_store_dword v237, v117, s[26:27] offset:4
	s_add_u32 s26, s26, 0x2c00
	s_addc_u32 s27, s27, 0
	global_store_dword v237, v121, s[26:27]
	global_store_dword v237, v113, s[26:27] offset:4
	s_add_u32 s26, s26, 0x2c00
	s_addc_u32 s27, s27, 0
	s_or_b64 exec, exec, s[16:17]
	s_branch .Lp8_side_done
